# HGRN chunk loop: q/v prefetch loads no longer waited right after issue (raw regs kept in flight one chunk)
# speedup vs baseline: 1.0115x; 1.0115x over previous
.LBB0_419:
	s_or_b64 exec, exec, s[16:17]
	v_lshlrev_b32_e32 v43, 16, v41
	v_mov_b32_e32 v41, v40
	v_pk_mul_f32 v[12:13], v[40:41], v[12:13] op_sel_hi:[0,1]
	v_pk_mul_f32 v[58:59], v[12:13], v[14:15]
	v_pk_mul_f32 v[12:13], v[40:41], v[16:17] op_sel_hi:[0,1]
	v_pk_mul_f32 v[62:63], v[12:13], v[20:21]
	v_pk_mul_f32 v[12:13], v[40:41], v[18:19] op_sel_hi:[0,1]
	v_pk_mul_f32 v[66:67], v[12:13], v[26:27]
	v_pk_mul_f32 v[12:13], v[40:41], v[22:23] op_sel_hi:[0,1]
	v_pk_mul_f32 v[70:71], v[12:13], v[24:25]
	v_pk_mul_f32 v[12:13], v[40:41], v[28:29] op_sel_hi:[0,1]
	v_pk_mul_f32 v[74:75], v[12:13], v[48:49]
	v_pk_mul_f32 v[12:13], v[40:41], v[36:37] op_sel_hi:[0,1]
	v_pk_mul_f32 v[78:79], v[12:13], v[50:51]
	v_pk_mul_f32 v[12:13], v[40:41], v[52:53] op_sel_hi:[0,1]
	v_pk_mul_f32 v[82:83], v[12:13], v[54:55]
	v_mul_f32_e32 v12, v42, v30
	v_med3_f32 v12, v12, s86, v230
	v_mul_f32_e32 v13, v44, v30
	s_and_b64 s[16:17], s[10:11], exec
	s_mov_b32 s1, 0x28484000
	v_med3_f32 v13, v13, s86, v230
	v_rcp_f32_e32 v14, v12
	s_cselect_b32 s1, s1, 0x2a484000
	v_rcp_f32_e32 v15, v13
	v_lshlrev_b32_e32 v56, 16, v56
	s_add_u32 s20, s80, s1
	s_movk_i32 s1, 0x1100
	v_mul_f32_e32 v12, v12, v43
	v_mul_f32_e32 v13, v13, v56
	v_mul_lo_u32 v119, v129, s1
	v_cvt_pk_bf16_f32 v13, v12, v13
	v_mul_f32_e32 v12, v47, v14
	v_add3_u32 v22, 0, v0, v119
	v_mul_f32_e32 v14, v59, v15
	v_cvt_pk_bf16_f32 v12, v12, v14
	ds_write_b16 v22, v13
	ds_write_b16_d16_hi v22, v13 offset:272
	ds_write_b16 v22, v12 offset:17408
	ds_write_b16_d16_hi v22, v12 offset:17680
	v_mul_f32_e32 v13, v46, v30
	v_med3_f32 v13, v13, s86, v230
	v_mul_f32_e32 v14, v106, v30
	v_med3_f32 v14, v14, s86, v230
	v_rcp_f32_e32 v15, v13
	v_rcp_f32_e32 v16, v14
	v_lshlrev_b32_e32 v57, 16, v57
	v_lshlrev_b32_e32 v60, 16, v60
	v_mul_f32_e32 v13, v13, v57
	v_mul_f32_e32 v14, v14, v60
	v_cvt_pk_bf16_f32 v14, v13, v14
	v_mul_f32_e32 v13, v58, v15
	v_mul_f32_e32 v15, v63, v16
	v_cvt_pk_bf16_f32 v13, v13, v15
	ds_write_b16 v22, v14 offset:544
	ds_write_b16_d16_hi v22, v14 offset:816
	ds_write_b16 v22, v13 offset:17952
	ds_write_b16_d16_hi v22, v13 offset:18224
	v_mul_f32_e32 v14, v107, v30
	v_med3_f32 v14, v14, s86, v230
	v_mul_f32_e32 v15, v108, v30
	v_med3_f32 v15, v15, s86, v230
	v_rcp_f32_e32 v16, v14
	v_rcp_f32_e32 v17, v15
	v_lshlrev_b32_e32 v61, 16, v61
	v_lshlrev_b32_e32 v64, 16, v64
	v_mul_f32_e32 v14, v14, v61
	v_mul_f32_e32 v15, v15, v64
	v_cvt_pk_bf16_f32 v15, v14, v15
	v_mul_f32_e32 v14, v62, v16
	v_mul_f32_e32 v16, v67, v17
	v_cvt_pk_bf16_f32 v14, v14, v16
	ds_write_b16 v22, v15 offset:1088
	ds_write_b16_d16_hi v22, v15 offset:1360
	ds_write_b16 v22, v14 offset:18496
	ds_write_b16_d16_hi v22, v14 offset:18768
	v_mul_f32_e32 v15, v109, v30
	v_med3_f32 v15, v15, s86, v230
	v_mul_f32_e32 v16, v110, v30
	v_med3_f32 v16, v16, s86, v230
	v_rcp_f32_e32 v17, v15
	v_rcp_f32_e32 v18, v16
	v_lshlrev_b32_e32 v65, 16, v65
	v_lshlrev_b32_e32 v68, 16, v68
	v_mul_f32_e32 v15, v15, v65
	v_mul_f32_e32 v16, v16, v68
	v_cvt_pk_bf16_f32 v16, v15, v16
	v_mul_f32_e32 v15, v66, v17
	v_mul_f32_e32 v17, v71, v18
	v_cvt_pk_bf16_f32 v15, v15, v17
	ds_write_b16 v22, v16 offset:1632
	ds_write_b16_d16_hi v22, v16 offset:1904
	ds_write_b16 v22, v15 offset:19040
	ds_write_b16_d16_hi v22, v15 offset:19312
	v_mul_f32_e32 v16, v111, v30
	v_med3_f32 v16, v16, s86, v230
	v_mul_f32_e32 v17, v112, v30
	v_med3_f32 v17, v17, s86, v230
	v_rcp_f32_e32 v18, v16
	v_rcp_f32_e32 v19, v17
	v_lshlrev_b32_e32 v69, 16, v69
	v_lshlrev_b32_e32 v72, 16, v72
	v_mul_f32_e32 v16, v16, v69
	v_mul_f32_e32 v17, v17, v72
	v_cvt_pk_bf16_f32 v17, v16, v17
	v_mul_f32_e32 v16, v70, v18
	v_mul_f32_e32 v18, v75, v19
	v_cvt_pk_bf16_f32 v16, v16, v18
	ds_write_b16 v22, v17 offset:2176
	ds_write_b16_d16_hi v22, v17 offset:2448
	ds_write_b16 v22, v16 offset:19584
	ds_write_b16_d16_hi v22, v16 offset:19856
	v_mul_f32_e32 v17, v113, v30
	v_med3_f32 v17, v17, s86, v230
	v_mul_f32_e32 v18, v114, v30
	v_med3_f32 v18, v18, s86, v230
	v_rcp_f32_e32 v19, v17
	v_rcp_f32_e32 v23, v18
	v_lshlrev_b32_e32 v73, 16, v73
	v_lshlrev_b32_e32 v76, 16, v76
	v_mul_f32_e32 v17, v17, v73
	v_mul_f32_e32 v18, v18, v76
	v_cvt_pk_bf16_f32 v18, v17, v18
	v_mul_f32_e32 v17, v74, v19
	v_mul_f32_e32 v19, v79, v23
	v_cvt_pk_bf16_f32 v17, v17, v19
	ds_write_b16 v22, v18 offset:2720
	ds_write_b16_d16_hi v22, v18 offset:2992
	ds_write_b16 v22, v17 offset:20128
	ds_write_b16_d16_hi v22, v17 offset:20400
	v_mul_f32_e32 v18, v115, v30
	v_med3_f32 v18, v18, s86, v230
	v_mul_f32_e32 v19, v116, v30
	v_med3_f32 v19, v19, s86, v230
	v_rcp_f32_e32 v23, v18
	v_rcp_f32_e32 v24, v19
	v_lshlrev_b32_e32 v77, 16, v77
	v_lshlrev_b32_e32 v80, 16, v80
	v_mul_f32_e32 v18, v18, v77
	v_mul_f32_e32 v19, v19, v80
	v_cvt_pk_bf16_f32 v19, v18, v19
	v_mul_f32_e32 v18, v78, v23
	v_mul_f32_e32 v23, v83, v24
	v_cvt_pk_bf16_f32 v18, v18, v23
	ds_write_b16 v22, v19 offset:3264
	ds_write_b16_d16_hi v22, v19 offset:3536
	ds_write_b16 v22, v18 offset:20672
	ds_write_b16_d16_hi v22, v18 offset:20944
	v_mul_f32_e32 v19, v117, v30
	v_med3_f32 v19, v19, s86, v230
	v_mul_f32_e32 v23, v118, v30
	v_med3_f32 v23, v23, s86, v230
	v_rcp_f32_e32 v24, v19
	v_rcp_f32_e32 v25, v23
	v_lshlrev_b32_e32 v81, 16, v81
	v_lshlrev_b32_e32 v84, 16, v84
	v_mul_f32_e32 v19, v19, v81
; #define LDS_BARRIER() do { asm volatile("s_waitcnt lgkmcnt(0)" ::: "memory"); __builtin_amdgcn_s_barrier(); asm volatile("" ::: "memory"); } while (0)
; __device__ __forceinline__ void hgrn_chain(const Params& p, LAS unsigned char* lds, int layer, int chain, int dvh) {
;     ...
;     HG_LOAD(0);
;     HG_A1(0);
;     HG_LOAD(1);
;     LDS_BARRIER();
;     HG_A2(0, lds);
;     LDS_BARRIER();
;     for (int c = 0; c < SEQ / 64; ++c) {
	v_mul_f32_e32 v23, v23, v84
	s_addc_u32 s21, s81, 0
	v_cvt_pk_bf16_f32 v23, v19, v23
	v_mul_f32_e32 v19, v82, v24
	v_mul_u32_u24_e32 v120, 0x90, v86
	v_lshlrev_b32_e32 v121, 5, v129
	s_movk_i32 s1, 0x480
	s_lshl_b32 s22, s56, 4
	v_lshrrev_b32_e32 v21, 4, v88
	v_mul_f32_e32 v24, v45, v25
	v_cvt_pk_bf16_f32 v19, v19, v24
	ds_write_b16 v22, v23 offset:3808
	ds_write_b16_d16_hi v22, v23 offset:4080
	ds_write_b16 v22, v19 offset:21216
	ds_write_b16_d16_hi v22, v19 offset:21488
	v_add3_u32 v22, 0, v120, v121
	v_lshlrev_b32_e32 v122, 1, v88
	v_mul_lo_u32 v123, v85, s1
	s_add_u32 s16, s90, s78
	ds_write_b128 v22, v[12:15] offset:34816
	ds_write_b128 v22, v[16:19] offset:34832
	v_add3_u32 v12, 0, v123, v122
	v_lshlrev_b32_e32 v14, 2, v21
	s_addc_u32 s17, s91, 0
	ds_write_b16 v12, v6 offset:53248
	ds_write_b16_d16_hi v12, v6 offset:53392
	ds_write_b16 v12, v7 offset:53536
	ds_write_b16_d16_hi v12, v7 offset:53680
	ds_write_b16 v12, v8 offset:53824
	ds_write_b16_d16_hi v12, v8 offset:53968
	ds_write_b16 v12, v9 offset:54112
	ds_write_b16_d16_hi v12, v9 offset:54256
	v_or_b32_e32 v12, s22, v14
	v_readlane_b32 s1, v255, 10
	s_add_u32 s0, s90, s0
	v_and_b32_e32 v20, 15, v39
	v_mov_b32_e32 v13, s1
	v_lshl_add_u32 v15, v12, 1, s1
	s_addc_u32 s1, s91, 0
	s_ashr_i32 s26, s56, 1
	s_lshl_b32 s57, s26, 4
	v_or_b32_e32 v16, s57, v20
	s_movk_i32 s59, 0x90
	v_lshl_add_u64 v[48:49], s[16:17], 0, v[0:1]
	s_lshl_b32 s16, s56, 1
	v_and_b32_e32 v124, 48, v39
	v_mul_lo_u32 v12, v16, s59
	v_lshlrev_b32_e32 v17, 3, v21
	v_readlane_b32 s17, v255, 11
	s_and_b32 s27, s16, 2
	s_and_b32 s16, s22, 48
	v_add3_u32 v126, s17, v12, v17
	v_add_u32_e32 v19, s17, v124
	s_lshl_b32 s17, s18, 2
	s_add_u32 s17, s20, s17
	s_addc_u32 s18, s21, 0
	s_lshl_b32 s19, s19, 2
	s_add_u32 s17, s17, s19
	v_or_b32_e32 v12, s16, v20
	s_addc_u32 s18, s18, 0
	s_lshl_b32 s16, s16, 2
	s_add_u32 s16, s17, s16
	s_addc_u32 s17, s18, 0
	s_movk_i32 s71, 0x110
	s_cmp_le_i32 s27, s26
	v_mul_u32_u24_e32 v127, 0x90, v12
	v_mad_u32_u24 v17, v12, s71, v13
	v_and_b32_e32 v12, 48, v88
	v_mov_b32_e32 v13, v1
	v_or_b32_e32 v18, s22, v20
	s_cselect_b64 s[74:75], -1, 0
	s_lshl_b32 s18, s27, 4
	s_lshl_b32 s73, s27, 5
	s_or_b32 s58, s27, 1
	v_lshl_add_u64 v[52:53], s[16:17], 0, v[12:13]
	s_movk_i32 s16, 0x7ff
	v_mul_lo_u32 v128, v18, s59
	v_or_b32_e32 v18, s18, v20
	s_cmp_lt_i32 s27, s26
	v_bitop3_b32 v13, v39, s16, 15 bitop3:0x6c
	v_cmp_eq_u32_e64 s[16:17], 3, v129
	v_mul_u32_u24_e32 v129, 0x110, v18
	v_or_b32_e32 v18, s18, v14
	s_cselect_b64 s[76:77], -1, 0
	s_lshl_b32 s56, s56, 6
	v_cmp_gt_i32_e64 s[18:19], v18, v16
	v_cmp_lt_i32_e64 s[20:21], v18, v16
	v_or_b32_e32 v22, 2, v18
	v_or_b32_e32 v18, 3, v18
	s_lshl_b32 s26, s58, 4
	s_add_i32 s56, s56, 0
	v_cmp_gt_i32_e64 s[24:25], v18, v16
	v_or_b32_e32 v18, s26, v20
	v_or_b32_e32 v14, s26, v14
	s_lshl_b32 s78, s58, 5
	s_and_b32 s58, s57, 0xffffffe0
	s_or_b32 s57, s57, 16
	s_add_i32 s56, s56, 0x25000
	s_waitcnt lgkmcnt(0)
	s_barrier
	v_lshl_add_u64 v[50:51], s[0:1], 0, v[0:1]
	v_mul_u32_u24_e32 v130, 0x110, v18
	v_cmp_gt_i32_e64 s[26:27], v14, v16
	v_cmp_lt_i32_e64 s[28:29], v14, v16
	v_or_b32_e32 v18, 2, v14
	v_or_b32_e32 v14, 3, v14
	v_or_b32_e32 v131, s58, v20
	v_or_b32_e32 v133, s57, v20
	s_add_u32 s0, s0, s70
	v_mul_lo_u32 v125, v16, s71
	v_mul_u32_u24_e32 v21, 0x110, v20
	v_cmp_gt_i32_e64 s[22:23], v22, v16
	v_cmp_gt_i32_e64 s[30:31], v18, v16
	v_cmp_gt_i32_e64 s[34:35], v14, v16
	v_mul_lo_u32 v14, v131, s59
	v_mul_lo_u32 v16, v133, s59
	s_addc_u32 s1, s1, 0
	v_mov_b32_e32 v18, 0
	s_mov_b32 s72, 0
	v_mul_lo_u32 v132, v131, s71
	v_mul_lo_u32 v134, v133, s71
	v_mul_u32_u24_e32 v135, 0x90, v20
	s_waitcnt vmcnt(1)
	v_perm_b32 v145, v145, v151, s87
	v_perm_b32 v146, v146, v150, s87
	v_perm_b32 v147, v147, v149, s87
	v_perm_b32 v148, v144, v148, s87
	v_perm_b32 v149, v142, v143, s87
	v_perm_b32 v150, v140, v141, s87
	v_perm_b32 v151, v138, v139, s87
	v_perm_b32 v152, v136, v137, s87
	v_mov_b32_e32 v39, v40
	v_add_u32_e32 v136, s56, v12
	v_lshl_add_u64 v[54:55], v[10:11], 1, s[0:1]
	v_xor_b32_e32 v137, 0x77f, v88
	v_sub_u32_e32 v138, 0x77f, v87
	v_subrev_u32_e32 v139, s57, v13
	v_subrev_u32_e32 v140, s58, v13
	v_add_u32_e32 v141, v15, v21
	v_add_u32_e32 v142, v17, v124
	v_add_u32_e32 v143, v19, v14
	v_add_u32_e32 v144, v19, v16
	s_mov_b32 s56, 0
	v_mov_b32_e32 v19, v18
	v_mov_b32_e32 v20, v18
	v_mov_b32_e32 v21, v18
	v_mov_b32_e32 v22, v18
	v_mov_b32_e32 v23, v18
	v_mov_b32_e32 v24, v18
	v_mov_b32_e32 v25, v18
	v_mov_b32_e32 v26, v18
	v_mov_b32_e32 v27, v18
	v_mov_b32_e32 v28, v18
	v_mov_b32_e32 v29, v18
	v_mov_b32_e32 v30, v18
	v_mov_b32_e32 v31, v18
	v_mov_b32_e32 v32, v18
	v_mov_b32_e32 v33, v18
	s_waitcnt vmcnt(0)
	v_mov_b64_e32 v[210:211], v[2:3]
	v_mov_b64_e32 v[212:213], v[4:5]
	v_lshrrev_b32_e32 v194, 16, v152
	v_mov_b32_e32 v195, v152
	v_lshrrev_b32_e32 v196, 16, v151
	v_mov_b32_e32 v197, v151
	v_lshrrev_b32_e32 v198, 16, v150
	v_mov_b32_e32 v199, v150
	v_lshrrev_b32_e32 v200, 16, v149
	v_mov_b32_e32 v201, v149
	v_lshrrev_b32_e32 v202, 16, v148
	v_mov_b32_e32 v203, v148
	v_lshrrev_b32_e32 v204, 16, v147
	v_mov_b32_e32 v205, v147
	v_lshrrev_b32_e32 v206, 16, v146
	v_mov_b32_e32 v207, v146
	v_lshrrev_b32_e32 v208, 16, v145
	v_mov_b32_e32 v209, v145
	s_branch .LBB0_422

; #define LAS __attribute__((address_space(3)))
; __device__ __forceinline__ unsigned pk2(float lo, float hi) { unsigned r; asm("v_cvt_pk_bf16_f32 %0, %1, %2" : "=v"(r) : "v"(lo), "v"(hi)); return r; }
; __device__ __forceinline__ void hgrn_chain(const Params& p, LAS unsigned char* lds, int layer, int chain, int dvh) {
;     ...
;                 u32x2 w; w.x = pk2(a4[0], a4[1]); w.y = pk2(a4[2], a4[3]);
;                 *(LAS u32x2*)(lds + H_PM + (tt * 16 + fr) * H_TS + (st * 16 + fq * 4) * 2) = w;
;             }
;         }
;         if (c + 1 < SEQ / 64) { HG_A1(cur ^ 1); if (c + 2 < SEQ / 64) HG_LOAD(c + 2); }
.LBB0_426:
	s_xor_b32 s57, s0, 1
	s_cmpk_lg_i32 s72, 0xf840
	v_cvt_pk_bf16_f32 v34, v35, v36
	v_add_u32_e32 v36, s78, v126
	s_cselect_b64 s[70:71], -1, 0
	s_cmpk_eq_i32 s72, 0xf840
	v_cvt_pk_bf16_f32 v35, v37, v85
	ds_write_b64 v36, v[34:35]
	s_cbranch_scc1 .LBB0_442
	s_waitcnt vmcnt(0)
	v_lshlrev_b32_e32 v34, 16, v92
	v_max_f32_e32 v34, v34, v34
	v_max_f32_e32 v34, 0xc2700000, v34
	v_mul_f32_e32 v34, 0xbfb8aa3b, v34
	v_exp_f32_e32 v63, v34
	v_lshlrev_b32_e32 v34, 16, v93
	v_max_f32_e32 v34, v34, v34
	v_max_f32_e32 v34, 0xc2700000, v34
	v_mul_f32_e32 v34, 0xbfb8aa3b, v34
	v_exp_f32_e32 v62, v34
	v_add_f32_e32 v34, 1.0, v63
	v_lshlrev_b32_e32 v43, 16, v96
	v_rcp_f32_e32 v65, v34
	v_add_f32_e32 v34, 1.0, v62
	v_max_f32_e32 v43, v43, v43
	v_rcp_f32_e32 v64, v34
	v_lshlrev_b32_e32 v34, 16, v95
	v_max_f32_e32 v43, 0xc2700000, v43
	v_max_f32_e32 v34, v34, v34
	v_mul_f32_e32 v43, 0xbfb8aa3b, v43
	v_max_f32_e32 v34, 0xc2700000, v34
	v_exp_f32_e32 v66, v43
	v_lshlrev_b32_e32 v43, 16, v97
	v_mul_f32_e32 v34, 0xbfb8aa3b, v34
	v_max_f32_e32 v43, v43, v43
	v_exp_f32_e32 v67, v34
	v_max_f32_e32 v43, 0xc2700000, v43
	v_mul_f32_e32 v43, 0xbfb8aa3b, v43
	v_exp_f32_e32 v71, v43
	v_add_f32_e32 v34, 1.0, v67
	v_rcp_f32_e32 v69, v34
	v_add_f32_e32 v34, 1.0, v66
	v_lshlrev_b32_e32 v43, 16, v99
	v_rcp_f32_e32 v68, v34
	v_add_f32_e32 v34, 1.0, v71
	v_max_f32_e32 v43, v43, v43
	v_rcp_f32_e32 v73, v34
	v_lshlrev_b32_e32 v34, 16, v98
	v_max_f32_e32 v43, 0xc2700000, v43
	v_max_f32_e32 v34, v34, v34
	v_mul_f32_e32 v43, 0xbfb8aa3b, v43
	v_max_f32_e32 v34, 0xc2700000, v34
	v_exp_f32_e32 v75, v43
	v_lshlrev_b32_e32 v43, 16, v100
	v_mul_f32_e32 v34, 0xbfb8aa3b, v34
	v_max_f32_e32 v43, v43, v43
	v_exp_f32_e32 v70, v34
	v_max_f32_e32 v43, 0xc2700000, v43
	v_mul_f32_e32 v43, 0xbfb8aa3b, v43
	v_exp_f32_e32 v74, v43
	v_add_f32_e32 v34, 1.0, v70
	v_rcp_f32_e32 v72, v34
	v_add_f32_e32 v34, 1.0, v75
	v_rcp_f32_e32 v77, v34
	v_add_f32_e32 v34, 1.0, v74
	v_rcp_f32_e32 v76, v34
	v_lshlrev_b32_e32 v34, 16, v101
	v_max_f32_e32 v34, v34, v34
	v_max_f32_e32 v34, 0xc2700000, v34
	v_lshlrev_b32_e32 v6, 16, v89
	v_mul_f32_e32 v34, 0xbfb8aa3b, v34
	v_max_f32_e32 v6, v6, v6
	v_exp_f32_e32 v79, v34
	v_max_f32_e32 v6, 0xc2700000, v6
	v_mul_f32_e32 v6, 0xbfb8aa3b, v6
	v_exp_f32_e32 v8, v6
	v_lshlrev_b32_e32 v6, 16, v90
	v_max_f32_e32 v6, v6, v6
	v_add_f32_e32 v34, 1.0, v79
	v_max_f32_e32 v6, 0xc2700000, v6
	v_rcp_f32_e32 v81, v34
	v_lshlrev_b32_e32 v34, 16, v102
	v_mul_f32_e32 v6, 0xbfb8aa3b, v6
	v_max_f32_e32 v34, v34, v34
	v_exp_f32_e32 v7, v6
	v_max_f32_e32 v34, 0xc2700000, v34
	v_lshlrev_b32_e32 v43, 16, v104
	v_mul_f32_e32 v34, 0xbfb8aa3b, v34
	v_max_f32_e32 v43, v43, v43
	v_exp_f32_e32 v78, v34
	v_lshlrev_b32_e32 v34, 16, v103
	v_max_f32_e32 v43, 0xc2700000, v43
	v_add_f32_e32 v6, 1.0, v8
	v_max_f32_e32 v34, v34, v34
	v_mul_f32_e32 v43, 0xbfb8aa3b, v43
	v_rcp_f32_e32 v35, v6
	v_add_f32_e32 v6, 1.0, v7
	v_max_f32_e32 v34, 0xc2700000, v34
	v_exp_f32_e32 v82, v43
	v_lshlrev_b32_e32 v43, 16, v105
	v_rcp_f32_e32 v9, v6
	v_lshlrev_b32_e32 v6, 16, v91
	v_mul_f32_e32 v34, 0xbfb8aa3b, v34
	v_max_f32_e32 v43, v43, v43
	v_max_f32_e32 v6, v6, v6
	v_exp_f32_e32 v83, v34
	v_max_f32_e32 v43, 0xc2700000, v43
	v_max_f32_e32 v6, 0xc2700000, v6
	v_mul_f32_e32 v43, 0xbfb8aa3b, v43
	v_mul_f32_e32 v6, 0xbfb8aa3b, v6
	v_exp_f32_e32 v45, v43
	v_exp_f32_e32 v6, v6
	v_add_f32_e32 v34, 1.0, v78
	v_rcp_f32_e32 v80, v34
	v_add_f32_e32 v34, 1.0, v83
	v_rcp_f32_e32 v85, v34
	v_add_f32_e32 v34, 1.0, v82
	v_rcp_f32_e32 v84, v34
	v_add_f32_e32 v34, 1.0, v45
	v_mul_f32_e32 v37, v40, v8
	v_add_f32_e32 v8, 1.0, v6
	v_rcp_f32_e32 v43, v34
	v_mul_f32_e32 v44, v40, v9
	v_rcp_f32_e32 v8, v8
	v_pk_add_f32 v[46:47], v[38:39], v[44:45]
	v_pk_mul_f32 v[44:45], v[38:39], v[44:45]
	v_fma_f32 v42, v40, v35, v38
	v_mov_b32_e32 v47, v45
	v_pk_mul_f32 v[44:45], v[46:47], v[42:43]
	v_fma_f32 v36, v40, v8, v38
	v_mov_b32_e32 v34, v44
	v_fma_f32 v56, v40, v65, v38
	v_pk_mul_f32 v[46:47], v[34:35], v[36:37]
	v_fma_f32 v57, v40, v64, v38
	v_mul_f32_e32 v106, v46, v56
	v_fma_f32 v58, v40, v69, v38
	v_mul_f32_e32 v107, v106, v57
	v_fma_f32 v59, v40, v68, v38
	v_mul_f32_e32 v108, v107, v58
	v_fma_f32 v60, v40, v73, v38
	v_mul_f32_e32 v109, v108, v59
	v_fma_f32 v61, v40, v72, v38
	v_mul_f32_e32 v110, v109, v60
	v_fma_f32 v112, v40, v77, v38
	v_mul_f32_e32 v111, v110, v61
	v_fma_f32 v113, v40, v76, v38
	v_mul_f32_e32 v112, v111, v112
	v_fma_f32 v114, v40, v81, v38
	v_mul_f32_e32 v113, v112, v113
	v_fma_f32 v115, v40, v80, v38
	v_mul_f32_e32 v114, v113, v114
	v_fma_f32 v116, v40, v85, v38
	v_mul_f32_e32 v115, v114, v115
	v_fma_f32 v117, v40, v84, v38
	v_mul_f32_e32 v116, v115, v116
	v_fma_f32 v118, v40, v43, v38
	v_mul_f32_e32 v117, v116, v117
	v_mul_f32_e32 v118, v117, v118
	v_lshl_add_u32 v34, s57, 11, v94
	ds_write_b32 v34, v118
	s_waitcnt vmcnt(0)
	s_cmp_gt_u32 s56, 29
	v_perm_b32 v152, v194, v195, s87
	v_perm_b32 v151, v196, v197, s87
	v_perm_b32 v150, v198, v199, s87
	v_perm_b32 v149, v200, v201, s87
	v_perm_b32 v148, v202, v203, s87
	v_perm_b32 v147, v204, v205, s87
	v_perm_b32 v146, v206, v207, s87
	v_perm_b32 v145, v208, v209, s87
	v_mov_b64_e32 v[2:3], v[210:211]
	v_mov_b64_e32 v[4:5], v[212:213]
	s_cbranch_scc1 .LBB0_441
	v_cndmask_b32_e64 v34, 0, 1, s[8:9]
	s_mov_b64 s[96:97], -1
	v_cmp_ne_u32_e64 s[0:1], 1, v34
	s_andn2_b64 vcc, exec, s[8:9]
	v_add_u32_e32 v34, s72, v138
	s_cbranch_vccnz .LBB0_432
	v_add_u32_e32 v36, s72, v138
	s_add_i32 s59, s56, 2
	v_lshl_add_u32 v35, s59, 6, v87
	s_cbranch_execz .LBB0_433

.LBB0_436:
	v_ashrrev_i32_e32 v37, 31, v36
	v_lshl_add_u64 v[36:37], s[4:5], 0, v[36:37]
	v_ashrrev_i32_e32 v35, 31, v34
	v_mad_u64_u32 v[56:57], s[96:97], v36, s38, v[48:49]
	v_lshl_add_u64 v[34:35], s[4:5], 0, v[34:35]
	v_mad_i32_i24 v57, v37, s38, v57
	v_mad_u64_u32 v[36:37], s[96:97], v34, s38, v[50:51]
	v_mad_i32_i24 v37, v35, s38, v37
	v_lshl_add_u64 v[34:35], v[56:57], 0, s[6:7]
	global_load_ushort v89, v[56:57], off
	global_load_ushort v194, v[36:37], off
	v_lshl_add_u64 v[36:37], v[36:37], 0, s[6:7]
	global_load_ushort v90, v[34:35], off
	global_load_ushort v195, v[36:37], off
	v_lshl_add_u64 v[34:35], v[34:35], 0, s[6:7]
	v_lshl_add_u64 v[36:37], v[36:37], 0, s[6:7]
	global_load_ushort v91, v[34:35], off
	global_load_ushort v196, v[36:37], off
	v_lshl_add_u64 v[34:35], v[34:35], 0, s[6:7]
	v_lshl_add_u64 v[36:37], v[36:37], 0, s[6:7]
	global_load_ushort v92, v[34:35], off
	global_load_ushort v197, v[36:37], off
	v_lshl_add_u64 v[34:35], v[34:35], 0, s[6:7]
	v_lshl_add_u64 v[36:37], v[36:37], 0, s[6:7]
	global_load_ushort v93, v[34:35], off
	global_load_ushort v198, v[36:37], off
	v_lshl_add_u64 v[34:35], v[34:35], 0, s[6:7]
	v_lshl_add_u64 v[36:37], v[36:37], 0, s[6:7]
	global_load_ushort v95, v[34:35], off
	global_load_ushort v199, v[36:37], off
	v_lshl_add_u64 v[34:35], v[34:35], 0, s[6:7]
	v_lshl_add_u64 v[36:37], v[36:37], 0, s[6:7]
	global_load_ushort v96, v[34:35], off
	global_load_ushort v200, v[36:37], off
	v_lshl_add_u64 v[34:35], v[34:35], 0, s[6:7]
	v_lshl_add_u64 v[36:37], v[36:37], 0, s[6:7]
	global_load_ushort v97, v[34:35], off
	global_load_ushort v201, v[36:37], off
	v_lshl_add_u64 v[34:35], v[34:35], 0, s[6:7]
	v_lshl_add_u64 v[36:37], v[36:37], 0, s[6:7]
	global_load_ushort v98, v[34:35], off
	global_load_ushort v202, v[36:37], off
	v_lshl_add_u64 v[34:35], v[34:35], 0, s[6:7]
	v_lshl_add_u64 v[36:37], v[36:37], 0, s[6:7]
	global_load_ushort v99, v[34:35], off
	global_load_ushort v203, v[36:37], off
	v_lshl_add_u64 v[34:35], v[34:35], 0, s[6:7]
	v_lshl_add_u64 v[36:37], v[36:37], 0, s[6:7]
	global_load_ushort v100, v[34:35], off
	global_load_ushort v204, v[36:37], off
	v_lshl_add_u64 v[34:35], v[34:35], 0, s[6:7]
	v_lshl_add_u64 v[36:37], v[36:37], 0, s[6:7]
	global_load_ushort v101, v[34:35], off
	global_load_ushort v205, v[36:37], off
	v_lshl_add_u64 v[34:35], v[34:35], 0, s[6:7]
	v_lshl_add_u64 v[36:37], v[36:37], 0, s[6:7]
	global_load_ushort v102, v[34:35], off
	global_load_ushort v206, v[36:37], off
	v_lshl_add_u64 v[34:35], v[34:35], 0, s[6:7]
	v_lshl_add_u64 v[36:37], v[36:37], 0, s[6:7]
	global_load_ushort v103, v[34:35], off
	global_load_ushort v207, v[36:37], off
	v_lshl_add_u64 v[34:35], v[34:35], 0, s[6:7]
	v_lshl_add_u64 v[36:37], v[36:37], 0, s[6:7]
	global_load_ushort v104, v[34:35], off
	global_load_ushort v208, v[36:37], off
	v_lshl_add_u64 v[34:35], v[34:35], 0, s[6:7]
	v_lshl_add_u64 v[36:37], v[36:37], 0, s[6:7]
	global_load_ushort v105, v[34:35], off
	global_load_ushort v209, v[36:37], off
	s_mov_b64 s[96:97], -1
	s_and_b64 vcc, exec, s[0:1]
	s_cbranch_vccnz .LBB0_438
	v_add_u32_e32 v34, s72, v137
	s_mov_b64 s[96:97], 0

.LBB0_440:
	v_ashrrev_i32_e32 v35, 31, v34
	v_lshl_add_u64 v[34:35], s[4:5], 0, v[34:35]
	v_mad_u64_u32 v[36:37], s[0:1], v34, s38, v[54:55]
	v_mad_i32_i24 v37, v35, s38, v37
	global_load_dwordx4 v[210:213], v[36:37], off offset:2048
.LBB0_441:
	v_pk_mul_f32 v[6:7], v[40:41], v[6:7]
	v_and_b32_e32 v43, 0xffff0000, v152
	v_pk_mul_f32 v[58:59], v[6:7], v[8:9]
	v_pk_mul_f32 v[6:7], v[40:41], v[62:63]
	v_lshlrev_b32_e32 v56, 16, v152
	v_pk_mul_f32 v[62:63], v[6:7], v[64:65]
	v_pk_mul_f32 v[6:7], v[40:41], v[66:67]
	v_and_b32_e32 v57, 0xffff0000, v151
	v_pk_mul_f32 v[66:67], v[6:7], v[68:69]
	v_pk_mul_f32 v[6:7], v[40:41], v[70:71]
	v_lshlrev_b32_e32 v60, 16, v151
	v_pk_mul_f32 v[70:71], v[6:7], v[72:73]
	v_pk_mul_f32 v[6:7], v[40:41], v[74:75]
	v_and_b32_e32 v61, 0xffff0000, v150
	v_pk_mul_f32 v[74:75], v[6:7], v[76:77]
	v_pk_mul_f32 v[6:7], v[40:41], v[78:79]
	v_lshlrev_b32_e32 v64, 16, v150
	v_pk_mul_f32 v[78:79], v[6:7], v[80:81]
	v_pk_mul_f32 v[6:7], v[40:41], v[82:83]
	v_and_b32_e32 v65, 0xffff0000, v149
	v_pk_mul_f32 v[82:83], v[6:7], v[84:85]
	v_mov_b64_e32 v[8:9], v[4:5]
	v_mov_b64_e32 v[6:7], v[2:3]
	v_lshlrev_b32_e32 v68, 16, v149
	v_and_b32_e32 v69, 0xffff0000, v148
	v_lshlrev_b32_e32 v72, 16, v148
	v_and_b32_e32 v73, 0xffff0000, v147
	v_lshlrev_b32_e32 v76, 16, v147
	v_and_b32_e32 v77, 0xffff0000, v146
	v_lshlrev_b32_e32 v80, 16, v146
	v_and_b32_e32 v81, 0xffff0000, v145
	v_lshlrev_b32_e32 v84, 16, v145
